# h_fold (P1) bf16 row stores write-through (sc1) on top of peel/noinv
# speedup vs baseline: 1.0119x; 1.0119x over previous
; __device__ __forceinline__ void pass_h_fold(const float* src, const float* g, const float* mod, bf16_t* H, bf16_t* HE, bf16_t* HO) {
;     ...
;     for (int ch = gw; ch < 2048; ch += NGW) {
;         const int b = ch >> 8, sb = (ch & 255) * 4;
;         f32x4 mul[4], sh[4];
; #pragma unroll
;         for (int j = 0; j < 4; ++j) { const f32x4 gg = ((const f32x4*)g)[lane + 64 * j], sc = ((const f32x4*)(mod + (size_t)b * NMOD + DM))[lane + 64 * j];
;             mul[j] = gg * (1.0f + sc); sh[j] = ((const f32x4*)(mod + (size_t)b * NMOD))[lane + 64 * j]; }
; #pragma unroll
;         for (int half = 0; half < 2; ++half) {
;             f32x4 v[2][2][4];
; #pragma unroll
;             for (int q = 0; q < 2; ++q) { const int s = sb + half * 2 + q, pr = (s == 0) ? SEQ / 2 : SEQ - s;
;                 const f32x4* x0 = (const f32x4*)(src + (size_t)(b * SEQ + s) * DM) + lane; const f32x4* x1 = (const f32x4*)(src + (size_t)(b * SEQ + pr) * DM) + lane;
; #pragma unroll
;                 for (int j = 0; j < 4; ++j) { v[q][0][j] = x0[64 * j]; v[q][1][j] = x1[64 * j]; } }
.LBB0_99:
	v_ashrrev_i32_e32 v16, 8, v173
	v_and_b32_e32 v17, 0x3fc, v180
	v_mul_hi_i32_i24_e32 v19, 0x6000, v16
	v_mul_i32_i24_e32 v18, 0x6000, v16
	v_lshlrev_b32_e32 v20, 11, v16
	v_lshlrev_b32_e32 v16, 10, v16
	v_or_b32_e32 v22, 1, v17
	v_or_b32_e32 v23, 2, v17
	v_or_b32_e32 v37, 3, v17
	v_lshl_add_u64 v[18:19], s[34:35], 0, v[18:19]
	v_or_b32_e32 v24, v17, v20
	v_sub_u32_e32 v21, 0x800, v17
	v_cmp_eq_u32_e64 s[4:5], 0, v17
	v_or_b32_e32 v26, v22, v20
	v_or_b32_e32 v28, v17, v16
	v_or_b32_e32 v30, v22, v16
	v_or_b32_e32 v32, v23, v20
	v_or_b32_e32 v34, v37, v20
	v_lshl_add_u64 v[40:41], v[18:19], 0, s[24:25]
	v_ashrrev_i32_e32 v25, 31, v24
	v_cndmask_b32_e64 v21, v21, v181, s[4:5]
	v_add_u32_e32 v39, 0x800, v20
	v_lshl_add_u64 v[42:43], v[18:19], 0, v[96:97]
	v_ashrrev_i32_e32 v27, 31, v26
	v_ashrrev_i32_e32 v29, 31, v28
	v_ashrrev_i32_e32 v31, 31, v30
	v_ashrrev_i32_e32 v33, 31, v32
	v_ashrrev_i32_e32 v35, 31, v34
	v_lshl_add_u64 v[52:53], v[40:41], 0, v[96:97]
	v_lshl_add_u64 v[54:55], v[40:41], 0, v[108:109]
	v_lshl_add_u64 v[56:57], v[40:41], 0, v[110:111]
	v_lshl_add_u64 v[40:41], v[40:41], 0, v[112:113]
	v_lshlrev_b64 v[58:59], 12, v[24:25]
	global_load_dwordx4 v[0:3], v[106:107], off
	global_load_dwordx4 v[4:7], v[106:107], off offset:1024
	global_load_dwordx4 v[8:11], v[106:107], off offset:2048
	global_load_dwordx4 v[12:15], v[106:107], off offset:3072
	v_or_b32_e32 v36, v23, v16
	v_or_b32_e32 v38, v37, v16
	v_add_u32_e32 v44, v21, v20
	v_sub_u32_e32 v46, v39, v22
	v_sub_u32_e32 v48, v39, v23
	v_sub_u32_e32 v50, v39, v37
	global_load_dwordx4 v[20:23], v[42:43], off offset:1024
	global_load_dwordx4 v[16:19], v[42:43], off offset:2048
	v_lshlrev_b64 v[60:61], 12, v[26:27]
	v_lshlrev_b64 v[62:63], 11, v[24:25]
	v_lshlrev_b64 v[64:65], 11, v[28:29]
	v_lshlrev_b64 v[66:67], 11, v[26:27]
	v_lshlrev_b64 v[68:69], 11, v[30:31]
	v_lshlrev_b64 v[70:71], 12, v[32:33]
	v_lshlrev_b64 v[72:73], 12, v[34:35]
	global_load_dwordx4 v[130:133], v[52:53], off
	global_load_dwordx4 v[28:31], v[42:43], off
	global_load_dwordx4 v[134:137], v[56:57], off
	global_load_dwordx4 v[138:141], v[40:41], off
	global_load_dwordx4 v[142:145], v[54:55], off
	global_load_dwordx4 v[24:27], v[42:43], off offset:3072
	v_lshl_add_u64 v[40:41], v[98:99], 0, v[58:59]
	v_ashrrev_i32_e32 v37, 31, v36
	v_ashrrev_i32_e32 v39, 31, v38
	v_ashrrev_i32_e32 v45, 31, v44
	v_ashrrev_i32_e32 v47, 31, v46
	v_ashrrev_i32_e32 v49, 31, v48
	v_ashrrev_i32_e32 v51, 31, v50
	v_lshlrev_b64 v[32:33], 11, v[32:33]
	v_lshlrev_b64 v[34:35], 11, v[34:35]
	v_lshl_add_u64 v[80:81], v[98:99], 0, v[60:61]
	v_lshl_add_u64 v[152:153], v[102:103], 0, v[68:69]
	v_lshl_add_u64 v[150:151], v[104:105], 0, v[68:69]
	v_lshl_add_u64 v[148:149], v[98:99], 0, v[70:71]
	v_lshl_add_u64 v[146:147], v[98:99], 0, v[72:73]
	global_load_dwordx4 v[84:87], v[40:41], off
	global_load_dwordx4 v[72:75], v[40:41], off offset:1024
	global_load_dwordx4 v[68:71], v[40:41], off offset:3072
	global_load_dwordx4 v[76:79], v[40:41], off offset:2048
	global_load_dwordx4 v[56:59], v[80:81], off
	v_lshlrev_b64 v[36:37], 11, v[36:37]
	v_lshlrev_b64 v[38:39], 11, v[38:39]
	v_lshlrev_b64 v[42:43], 12, v[44:45]
	v_lshlrev_b64 v[82:83], 12, v[46:47]
	v_lshl_add_u64 v[166:167], v[100:101], 0, v[62:63]
	v_lshl_add_u64 v[164:165], v[102:103], 0, v[64:65]
	v_lshl_add_u64 v[162:163], v[104:105], 0, v[64:65]
	v_lshl_add_u64 v[154:155], v[100:101], 0, v[66:67]
	v_lshlrev_b64 v[64:65], 12, v[48:49]
	v_lshlrev_b64 v[66:67], 12, v[50:51]
	v_lshl_add_u64 v[126:127], v[100:101], 0, v[32:33]
	v_lshlrev_b64 v[32:33], 11, v[48:49]
	v_lshl_add_u64 v[118:119], v[100:101], 0, v[34:35]
	v_lshlrev_b64 v[34:35], 11, v[50:51]
	global_load_dwordx4 v[60:63], v[80:81], off offset:1024
	global_load_dwordx4 v[52:55], v[80:81], off offset:2048
	global_load_dwordx4 v[48:51], v[80:81], off offset:3072
	v_lshlrev_b64 v[44:45], 11, v[44:45]
	v_lshlrev_b64 v[46:47], 11, v[46:47]
	v_lshl_add_u64 v[124:125], v[102:103], 0, v[36:37]
	v_lshl_add_u64 v[122:123], v[104:105], 0, v[36:37]
	v_lshl_add_u64 v[116:117], v[102:103], 0, v[38:39]
	v_lshl_add_u64 v[114:115], v[104:105], 0, v[38:39]
	v_lshl_add_u64 v[36:37], v[98:99], 0, v[42:43]
	v_lshl_add_u64 v[38:39], v[98:99], 0, v[82:83]
	v_lshl_add_u64 v[168:169], v[100:101], 0, v[44:45]
	v_lshl_add_u64 v[160:161], v[100:101], 0, v[46:47]
	v_lshl_add_u64 v[158:159], v[98:99], 0, v[64:65]
	v_lshl_add_u64 v[156:157], v[98:99], 0, v[66:67]
	v_lshl_add_u64 v[128:129], v[100:101], 0, v[32:33]
	v_lshl_add_u64 v[120:121], v[100:101], 0, v[34:35]
	global_load_dwordx4 v[92:95], v[36:37], off
	global_load_dwordx4 v[88:91], v[36:37], off offset:1024
	global_load_dwordx4 v[64:67], v[36:37], off offset:3072
	global_load_dwordx4 v[80:83], v[36:37], off offset:2048
	global_load_dwordx4 v[44:47], v[38:39], off
	global_load_dwordx4 v[40:43], v[38:39], off offset:1024
	global_load_dwordx4 v[32:35], v[38:39], off offset:3072
	s_nop 0
	global_load_dwordx4 v[36:39], v[38:39], off offset:2048
	v_add_u32_e32 v173, s26, v173
	v_cmp_lt_i32_e32 vcc, s41, v173
	s_or_b64 s[22:23], vcc, s[22:23]
	v_add_u32_e32 v180, s27, v180
	s_waitcnt vmcnt(21)
	v_pk_add_f32 v[132:133], v[132:133], 1.0 op_sel_hi:[1,0]
	v_pk_add_f32 v[184:185], v[130:131], 1.0 op_sel_hi:[1,0]
	s_waitcnt vmcnt(19)
	v_pk_add_f32 v[186:187], v[136:137], 1.0 op_sel_hi:[1,0]
	v_pk_add_f32 v[188:189], v[134:135], 1.0 op_sel_hi:[1,0]
	s_waitcnt vmcnt(17)
; __device__ __forceinline__ void pass_h_fold(const float* src, const float* g, const float* mod, bf16_t* H, bf16_t* HE, bf16_t* HO) {
;     ...
;         for (int j = 0; j < 4; ++j) { const f32x4 gg = ((const f32x4*)g)[lane + 64 * j], sc = ((const f32x4*)(mod + (size_t)b * NMOD + DM))[lane + 64 * j];
;             mul[j] = gg * (1.0f + sc); sh[j] = ((const f32x4*)(mod + (size_t)b * NMOD))[lane + 64 * j]; }
;     ...
;                 float t0 = 0.f, t1 = 0.f;
; #pragma unroll
;                 for (int j = 0; j < 4; ++j) { const f32x4 a = v[q][0][j], c = v[q][1][j]; t0 += (a[0] * a[0] + a[1] * a[1]) + (a[2] * a[2] + a[3] * a[3]); t1 += (c[0] * c[0] + c[1] * c[1]) + (c[2] * c[2] + c[3] * c[3]); }
	v_pk_add_f32 v[144:145], v[144:145], 1.0 op_sel_hi:[1,0]
	v_pk_add_f32 v[142:143], v[142:143], 1.0 op_sel_hi:[1,0]
	v_pk_add_f32 v[190:191], v[140:141], 1.0 op_sel_hi:[1,0]
	v_pk_add_f32 v[192:193], v[138:139], 1.0 op_sel_hi:[1,0]
	v_pk_mul_f32 v[130:131], v[2:3], v[132:133]
	v_pk_mul_f32 v[132:133], v[0:1], v[184:185]
	v_pk_mul_f32 v[134:135], v[6:7], v[144:145]
	v_pk_mul_f32 v[136:137], v[4:5], v[142:143]
	v_pk_mul_f32 v[138:139], v[10:11], v[186:187]
	v_pk_mul_f32 v[140:141], v[8:9], v[188:189]
	v_pk_mul_f32 v[142:143], v[14:15], v[190:191]
	v_pk_mul_f32 v[144:145], v[12:13], v[192:193]
	s_waitcnt vmcnt(15)
	v_pk_mul_f32 v[0:1], v[86:87], v[86:87]
	v_pk_mul_f32 v[2:3], v[84:85], v[84:85]
	s_waitcnt vmcnt(14)
	v_pk_mul_f32 v[4:5], v[74:75], v[74:75]
	v_pk_mul_f32 v[6:7], v[72:73], v[72:73]
	s_waitcnt vmcnt(12)
	v_mul_f32_e32 v8, v77, v77
	v_mul_f32_e32 v10, v79, v79
	s_waitcnt vmcnt(11)
	v_pk_mul_f32 v[12:13], v[58:59], v[58:59]
	v_pk_mul_f32 v[14:15], v[56:57], v[56:57]
	v_pk_mov_b32 v[192:193], v[2:3], v[0:1] op_sel:[1,0]
	v_mov_b32_e32 v3, v1
	v_pk_mov_b32 v[196:197], v[6:7], v[4:5] op_sel:[1,0]
	v_mov_b32_e32 v7, v5
	v_mul_f32_e32 v201, v70, v70
	v_mul_f32_e32 v203, v71, v71
	v_pk_fma_f32 v[8:9], v[76:77], v[76:77], v[8:9] op_sel_hi:[1,1,0]
	v_pk_fma_f32 v[10:11], v[78:79], v[78:79], v[10:11] op_sel_hi:[1,1,0]
	v_pk_mov_b32 v[204:205], v[14:15], v[12:13] op_sel:[1,0]
	s_waitcnt vmcnt(10)
	v_pk_mul_f32 v[184:185], v[62:63], v[62:63]
	v_pk_mul_f32 v[186:187], v[60:61], v[60:61]
	s_waitcnt vmcnt(9)
	v_mul_f32_e32 v188, v53, v53
	v_mul_f32_e32 v190, v55, v55
	s_waitcnt vmcnt(8)
	v_mul_f32_e32 v218, v50, v50
	v_mul_f32_e32 v219, v51, v51
	v_mov_b32_e32 v15, v13
	v_pk_mov_b32 v[208:209], v[186:187], v[184:185] op_sel:[1,0]
	v_mov_b32_e32 v187, v185
	v_pk_fma_f32 v[188:189], v[52:53], v[52:53], v[188:189] op_sel_hi:[1,1,0]
	s_waitcnt vmcnt(7)
	v_pk_mul_f32 v[0:1], v[94:95], v[94:95]
	v_pk_mul_f32 v[194:195], v[92:93], v[92:93]
	s_waitcnt vmcnt(6)
	v_pk_mul_f32 v[4:5], v[90:91], v[90:91]
	v_pk_mul_f32 v[198:199], v[88:89], v[88:89]
	s_waitcnt vmcnt(4)
	v_mul_f32_e32 v200, v81, v81
	s_waitcnt vmcnt(3)
	v_pk_mul_f32 v[12:13], v[46:47], v[46:47]
	v_pk_mul_f32 v[206:207], v[44:45], v[44:45]
	s_waitcnt vmcnt(2)
	v_pk_mul_f32 v[184:185], v[42:43], v[42:43]
	v_pk_mul_f32 v[210:211], v[40:41], v[40:41]
	v_pk_fma_f32 v[190:191], v[54:55], v[54:55], v[190:191] op_sel_hi:[1,1,0]
	v_pk_add_f32 v[2:3], v[192:193], v[2:3]
	v_pk_mov_b32 v[192:193], v[194:195], v[0:1] op_sel:[1,0]
	v_mov_b32_e32 v195, v1
	v_pk_add_f32 v[0:1], v[196:197], v[6:7]
	v_pk_mov_b32 v[6:7], v[198:199], v[4:5] op_sel:[1,0]
	v_mov_b32_e32 v199, v5
	v_mul_f32_e32 v213, v68, v68
	v_mul_f32_e32 v215, v69, v69
	v_mul_f32_e32 v202, v83, v83
	v_mov_b32_e32 v9, v201
	v_mov_b32_e32 v11, v203
	v_pk_fma_f32 v[4:5], v[80:81], v[80:81], v[200:201] op_sel_hi:[1,1,0]
	v_pk_add_f32 v[14:15], v[204:205], v[14:15]
	v_pk_mov_b32 v[200:201], v[206:207], v[12:13] op_sel:[1,0]
	v_mov_b32_e32 v207, v13
	v_pk_add_f32 v[12:13], v[208:209], v[186:187]
	v_pk_mov_b32 v[186:187], v[210:211], v[184:185] op_sel:[1,0]
	v_mov_b32_e32 v211, v185
	v_mov_b32_e32 v189, v218
	v_mov_b32_e32 v191, v219
	v_pk_add_f32 v[192:193], v[192:193], v[194:195]
	v_pk_add_f32 v[6:7], v[6:7], v[198:199]
	v_pk_add_f32 v[2:3], v[2:3], v[2:3] op_sel:[0,1] op_sel_hi:[1,0]
	v_pk_add_f32 v[0:1], v[0:1], v[0:1] op_sel:[0,1] op_sel_hi:[1,0]
	v_mul_f32_e32 v216, v48, v48
	v_mul_f32_e32 v217, v49, v49
	v_mul_f32_e32 v220, v64, v64
	v_mul_f32_e32 v221, v65, v65
	v_mul_f32_e32 v222, v66, v66
	v_mul_f32_e32 v223, v67, v67
	v_pk_fma_f32 v[196:197], v[82:83], v[82:83], v[202:203] op_sel_hi:[1,1,0]
	v_pk_add_f32 v[8:9], v[8:9], v[10:11]
	v_pk_add_f32 v[10:11], v[200:201], v[206:207]
	v_pk_add_f32 v[186:187], v[186:187], v[210:211]
	v_pk_add_f32 v[14:15], v[14:15], v[14:15] op_sel:[0,1] op_sel_hi:[1,0]
	v_pk_add_f32 v[12:13], v[12:13], v[12:13] op_sel:[0,1] op_sel_hi:[1,0]
	v_pk_add_f32 v[188:189], v[188:189], v[190:191]
	v_mov_b32_e32 v3, v213
	v_mov_b32_e32 v1, v215
	v_pk_add_f32 v[190:191], v[192:193], v[192:193] op_sel:[0,1] op_sel_hi:[1,0]
	v_pk_add_f32 v[6:7], v[6:7], v[6:7] op_sel:[0,1] op_sel_hi:[1,0]
	s_waitcnt vmcnt(1)
	v_mul_f32_e32 v224, v32, v32
	v_mul_f32_e32 v225, v33, v33
	s_waitcnt vmcnt(0)
	v_mul_f32_e32 v212, v37, v37
	v_mul_f32_e32 v214, v39, v39
	v_mov_b32_e32 v5, v222
	v_mov_b32_e32 v197, v223
	v_mov_b32_e32 v15, v216
	v_mov_b32_e32 v13, v217
	v_pk_add_f32 v[10:11], v[10:11], v[10:11] op_sel:[0,1] op_sel_hi:[1,0]
	v_pk_add_f32 v[186:187], v[186:187], v[186:187] op_sel:[0,1] op_sel_hi:[1,0]
	v_pk_add_f32 v[0:1], v[2:3], v[0:1]
	v_mov_b32_e32 v191, v220
	v_mov_b32_e32 v7, v221
	v_mul_f32_e32 v226, v34, v34
	v_mul_f32_e32 v227, v35, v35
	v_pk_fma_f32 v[184:185], v[36:37], v[36:37], v[212:213] op_sel_hi:[1,1,0]
	v_pk_fma_f32 v[202:203], v[38:39], v[38:39], v[214:215] op_sel_hi:[1,1,0]
	v_pk_add_f32 v[4:5], v[4:5], v[196:197]
	v_pk_add_f32 v[2:3], v[14:15], v[12:13]
	v_mov_b32_e32 v11, v224
	v_mov_b32_e32 v187, v225
	v_pk_add_f32 v[0:1], v[0:1], v[8:9]
	v_pk_add_f32 v[6:7], v[190:191], v[6:7]
	v_mov_b32_e32 v185, v226
	v_mov_b32_e32 v203, v227
	v_pk_add_f32 v[2:3], v[2:3], v[188:189]
	v_pk_add_f32 v[8:9], v[10:11], v[186:187]
	v_add_f32_e32 v10, v0, v1
	v_pk_add_f32 v[0:1], v[6:7], v[4:5]
	v_pk_add_f32 v[184:185], v[184:185], v[202:203]
	v_add_f32_e32 v4, v2, v3
	v_add_f32_e32 v0, v0, v1
	ds_bpermute_b32 v1, v174, v10
	v_pk_add_f32 v[2:3], v[8:9], v[184:185]
	ds_bpermute_b32 v5, v174, v4
	v_add_f32_e32 v2, v2, v3
	ds_bpermute_b32 v3, v174, v0
	ds_bpermute_b32 v6, v174, v2
	s_waitcnt lgkmcnt(3)
	v_add_f32_e32 v1, v10, v1
	s_waitcnt lgkmcnt(2)
; __device__ __forceinline__ float wave_sum(float v) {
; #pragma unroll
;     for (int o = 1; o < 64; o <<= 1) v += __shfl_xor(v, o);
;     return v;
; __device__ __forceinline__ void pass_h_fold(const float* src, const float* g, const float* mod, bf16_t* H, bf16_t* HE, bf16_t* HO) {
;     ...
;                 t0 = wave_sum(t0); t1 = wave_sum(t1);
;                 const float r0 = 1.0f / sqrtf(t0 * (1.0f / DM) + EPS), r1 = 1.0f / sqrtf(t1 * (1.0f / DM) + EPS);
	v_add_f32_e32 v4, v4, v5
	ds_bpermute_b32 v5, v175, v1
	s_waitcnt lgkmcnt(2)
	v_add_f32_e32 v0, v0, v3
	ds_bpermute_b32 v3, v175, v4
	s_waitcnt lgkmcnt(2)
	v_add_f32_e32 v2, v2, v6
	ds_bpermute_b32 v6, v175, v0
	ds_bpermute_b32 v7, v175, v2
	s_waitcnt lgkmcnt(3)
	v_add_f32_e32 v1, v1, v5
	s_waitcnt lgkmcnt(2)
	v_add_f32_e32 v3, v4, v3
	ds_bpermute_b32 v4, v176, v1
	s_waitcnt lgkmcnt(2)
	v_add_f32_e32 v0, v0, v6
	ds_bpermute_b32 v5, v176, v3
	s_waitcnt lgkmcnt(2)
	v_add_f32_e32 v2, v2, v7
	ds_bpermute_b32 v6, v176, v0
	ds_bpermute_b32 v7, v176, v2
	s_waitcnt lgkmcnt(3)
	v_add_f32_e32 v1, v1, v4
	s_waitcnt lgkmcnt(2)
	v_add_f32_e32 v3, v3, v5
	ds_bpermute_b32 v4, v177, v1
	s_waitcnt lgkmcnt(2)
	v_add_f32_e32 v0, v0, v6
	ds_bpermute_b32 v5, v177, v3
	s_waitcnt lgkmcnt(2)
	v_add_f32_e32 v2, v2, v7
	ds_bpermute_b32 v6, v177, v0
	ds_bpermute_b32 v7, v177, v2
	s_waitcnt lgkmcnt(3)
	v_add_f32_e32 v1, v1, v4
	s_waitcnt lgkmcnt(2)
	v_add_f32_e32 v3, v3, v5
	ds_bpermute_b32 v4, v178, v1
	s_waitcnt lgkmcnt(2)
	v_add_f32_e32 v0, v0, v6
	ds_bpermute_b32 v5, v178, v3
	s_waitcnt lgkmcnt(2)
	v_add_f32_e32 v2, v2, v7
	ds_bpermute_b32 v6, v178, v0
	ds_bpermute_b32 v7, v178, v2
	s_waitcnt lgkmcnt(3)
	v_add_f32_e32 v1, v1, v4
	s_waitcnt lgkmcnt(2)
	v_add_f32_e32 v3, v3, v5
	ds_bpermute_b32 v4, v179, v1
	s_waitcnt lgkmcnt(2)
	v_add_f32_e32 v0, v0, v6
	ds_bpermute_b32 v5, v179, v3
	s_waitcnt lgkmcnt(2)
	v_add_f32_e32 v2, v2, v7
	ds_bpermute_b32 v6, v179, v0
	ds_bpermute_b32 v7, v179, v2
	s_waitcnt lgkmcnt(3)
	v_add_f32_e32 v1, v1, v4
	s_waitcnt lgkmcnt(2)
	v_add_f32_e32 v3, v3, v5
	v_fmamk_f32 v1, v1, 0x3a800000, v182
	s_waitcnt lgkmcnt(1)
	v_add_f32_e32 v0, v0, v6
	v_fmamk_f32 v3, v3, 0x3a800000, v182
	v_mul_f32_e32 v4, 0x4f800000, v1
	v_cmp_gt_f32_e64 s[6:7], s40, v1
	s_waitcnt lgkmcnt(0)
	v_add_f32_e32 v2, v2, v7
	v_fmamk_f32 v0, v0, 0x3a800000, v182
	v_mul_f32_e32 v5, 0x4f800000, v3
	v_cmp_gt_f32_e32 vcc, s40, v3
	v_cndmask_b32_e64 v1, v1, v4, s[6:7]
	v_fmamk_f32 v2, v2, 0x3a800000, v182
	v_mul_f32_e32 v4, 0x4f800000, v0
	v_cmp_gt_f32_e64 s[8:9], s40, v0
	v_cndmask_b32_e32 v3, v3, v5, vcc
	v_sqrt_f32_e32 v6, v1
	v_mul_f32_e32 v5, 0x4f800000, v2
	v_cmp_gt_f32_e64 s[12:13], s40, v2
	v_cndmask_b32_e64 v0, v0, v4, s[8:9]
	v_sqrt_f32_e32 v4, v3
	v_cndmask_b32_e64 v2, v2, v5, s[12:13]
	v_sqrt_f32_e32 v5, v0
	v_sqrt_f32_e32 v7, v2
	v_add_u32_e32 v8, -1, v6
	v_add_u32_e32 v9, 1, v6
	v_add_u32_e32 v10, -1, v4
	v_fma_f32 v12, -v8, v6, v1
	v_add_u32_e32 v11, 1, v4
	v_fma_f32 v13, -v9, v6, v1
	v_add_u32_e32 v14, -1, v5
	v_fma_f32 v184, -v10, v4, v3
	v_cmp_ge_f32_e64 s[14:15], 0, v12
	v_add_u32_e32 v15, 1, v5
	v_fma_f32 v185, -v11, v4, v3
	v_add_u32_e32 v186, -1, v7
	v_cndmask_b32_e64 v6, v6, v8, s[14:15]
	v_fma_f32 v8, -v14, v5, v0
	v_cmp_ge_f32_e64 s[14:15], 0, v184
	v_cmp_lt_f32_e64 s[16:17], 0, v13
	v_add_u32_e32 v187, 1, v7
	v_fma_f32 v12, -v15, v5, v0
	v_cndmask_b32_e64 v4, v4, v10, s[14:15]
	v_cmp_lt_f32_e64 s[14:15], 0, v185
	v_fma_f32 v10, -v186, v7, v2
	v_cndmask_b32_e64 v6, v6, v9, s[16:17]
	v_cmp_ge_f32_e64 s[16:17], 0, v8
	v_fma_f32 v184, -v187, v7, v2
	v_cndmask_b32_e64 v4, v4, v11, s[14:15]
	v_cndmask_b32_e64 v5, v5, v14, s[16:17]
	v_cmp_lt_f32_e64 s[16:17], 0, v12
	v_cmp_ge_f32_e64 s[14:15], 0, v10
	v_mul_f32_e32 v8, 0x37800000, v6
	v_cndmask_b32_e64 v5, v5, v15, s[16:17]
	v_cndmask_b32_e64 v7, v7, v186, s[14:15]
	v_cmp_lt_f32_e64 s[14:15], 0, v184
	v_mul_f32_e32 v9, 0x37800000, v4
	v_cndmask_b32_e64 v6, v6, v8, s[6:7]
	v_cndmask_b32_e64 v7, v7, v187, s[14:15]
	v_mul_f32_e32 v8, 0x37800000, v5
	v_cmp_class_f32_e64 s[6:7], v1, v183
	v_cndmask_b32_e32 v4, v4, v9, vcc
	v_cmp_class_f32_e32 vcc, v3, v183
	v_mul_f32_e32 v9, 0x37800000, v7
	v_cndmask_b32_e64 v1, v6, v1, s[6:7]
	v_cndmask_b32_e64 v5, v5, v8, s[8:9]
	v_cmp_class_f32_e64 s[6:7], v0, v183
	v_cndmask_b32_e32 v184, v4, v3, vcc
	v_cndmask_b32_e64 v3, v7, v9, s[12:13]
	v_cmp_class_f32_e32 vcc, v2, v183
	v_div_scale_f32 v4, s[8:9], v1, v1, 1.0
	v_cndmask_b32_e64 v5, v5, v0, s[6:7]
	v_div_scale_f32 v0, s[6:7], v184, v184, 1.0
	v_cndmask_b32_e32 v185, v3, v2, vcc
	v_rcp_f32_e32 v2, v4
	v_div_scale_f32 v3, s[10:11], v5, v5, 1.0
	v_rcp_f32_e32 v186, v0
	v_div_scale_f32 v9, s[10:11], v185, v185, 1.0
	v_rcp_f32_e32 v11, v3
	v_rcp_f32_e32 v187, v9
	v_fma_f32 v12, -v4, v2, 1.0
	v_div_scale_f32 v6, s[8:9], 1.0, v1, 1.0
	v_fma_f32 v13, -v0, v186, 1.0
	v_fmac_f32_e32 v2, v12, v2
	v_fma_f32 v12, -v3, v11, 1.0
	v_div_scale_f32 v7, s[6:7], 1.0, v184, 1.0
	v_div_scale_f32 v8, s[12:13], 1.0, v5, 1.0
	v_fmac_f32_e32 v186, v13, v186
	v_fma_f32 v13, -v9, v187, 1.0
	v_mul_f32_e32 v14, v6, v2
	v_fmac_f32_e32 v11, v12, v11
	v_mul_f32_e32 v188, v7, v186
	v_fmac_f32_e32 v187, v13, v187
	v_fma_f32 v12, -v4, v14, v6
	v_mul_f32_e32 v13, v8, v11
	v_fma_f32 v15, -v0, v188, v7
	v_fmac_f32_e32 v14, v12, v2
	v_fma_f32 v12, -v3, v13, v8
	v_div_scale_f32 v10, s[14:15], 1.0, v185, 1.0
	v_fmac_f32_e32 v188, v15, v186
	v_fma_f32 v4, -v4, v14, v6
	v_fmac_f32_e32 v13, v12, v11
	s_mov_b64 vcc, s[8:9]
	v_mul_f32_e32 v189, v10, v187
	v_fma_f32 v190, -v0, v188, v7
	v_div_fmas_f32 v0, v4, v2, v14
	v_fma_f32 v2, -v3, v13, v8
	s_mov_b64 vcc, s[12:13]
	v_fma_f32 v15, -v9, v189, v10
	v_div_fixup_f32 v0, v0, v1, 1.0
	v_div_fmas_f32 v1, v2, v11, v13
	v_fmac_f32_e32 v189, v15, v187
	v_div_fixup_f32 v2, v1, v5, 1.0
	s_mov_b64 vcc, s[6:7]
	v_fma_f32 v191, -v9, v189, v10
	v_pk_mul_f32 v[4:5], v[84:85], v[0:1] op_sel_hi:[1,0]
	v_pk_mul_f32 v[6:7], v[86:87], v[0:1] op_sel_hi:[1,0]
	v_pk_mul_f32 v[8:9], v[72:73], v[0:1] op_sel_hi:[1,0]
	v_pk_mul_f32 v[10:11], v[74:75], v[0:1] op_sel_hi:[1,0]
	v_pk_mul_f32 v[12:13], v[76:77], v[0:1] op_sel_hi:[1,0]
; __device__ __forceinline__ unsigned cvt_pk_bf16(float lo, float hi) { unsigned r; asm volatile("v_cvt_pk_bf16_f32 %0, %1, %2" : "=v"(r) : "v"(lo), "v"(hi)); return r; }
; __device__ __forceinline__ void pass_h_fold(const float* src, const float* g, const float* mod, bf16_t* H, bf16_t* HE, bf16_t* HO) {
;     ...
;                 u32x2* o0 = (u32x2*)(H + (size_t)(b * SEQ + s) * DM) + lane; u32x2* o1 = (u32x2*)(H + (size_t)(b * SEQ + pr) * DM) + lane;
;                 u32x2* oe = (u32x2*)(HE + (size_t)(b * 1024 + s) * DM) + lane; u32x2* oo = (u32x2*)(HO + (size_t)(b * 1024 + s) * DM) + lane;
; #pragma unroll
;                 for (int j = 0; j < 4; ++j) { const f32x4 h0 = (v[q][0][j] * r0) * mul[j] + sh[j], h1 = (v[q][1][j] * r1) * mul[j] + sh[j];
;                     u32x2 w; w.x = cvt_pk_bf16(h0[0], h0[1]); w.y = cvt_pk_bf16(h0[2], h0[3]); o0[64 * j] = w;
;                     w.x = cvt_pk_bf16(h1[0], h1[1]); w.y = cvt_pk_bf16(h1[2], h1[3]); o1[64 * j] = w;
;                     const f32x4 e = (s == 0) ? h0 : h0 + h1, o = (s == 0) ? (f32x4){0.f, 0.f, 0.f, 0.f} : h0 - h1;
;                     w.x = cvt_pk_bf16(e[0], e[1]); w.y = cvt_pk_bf16(e[2], e[3]); oe[64 * j] = w;
;                     w.x = cvt_pk_bf16(o[0], o[1]); w.y = cvt_pk_bf16(o[2], o[3]); oo[64 * j] = w; } }
	v_pk_mul_f32 v[14:15], v[78:79], v[0:1] op_sel_hi:[1,0]
	v_pk_mul_f32 v[68:69], v[68:69], v[0:1] op_sel_hi:[1,0]
	v_pk_mul_f32 v[0:1], v[70:71], v[0:1] op_sel_hi:[1,0]
	v_div_fmas_f32 v84, v190, v186, v188
	v_pk_mul_f32 v[70:71], v[92:93], v[2:3] op_sel_hi:[1,0]
	s_mov_b64 vcc, s[14:15]
	v_pk_fma_f32 v[4:5], v[132:133], v[4:5], v[28:29]
	v_pk_mul_f32 v[72:73], v[94:95], v[2:3] op_sel_hi:[1,0]
	v_pk_mul_f32 v[74:75], v[88:89], v[2:3] op_sel_hi:[1,0]
	v_pk_mul_f32 v[76:77], v[90:91], v[2:3] op_sel_hi:[1,0]
	v_pk_mul_f32 v[78:79], v[80:81], v[2:3] op_sel_hi:[1,0]
	v_pk_mul_f32 v[80:81], v[82:83], v[2:3] op_sel_hi:[1,0]
	v_pk_mul_f32 v[64:65], v[64:65], v[2:3] op_sel_hi:[1,0]
	v_pk_mul_f32 v[2:3], v[66:67], v[2:3] op_sel_hi:[1,0]
	v_div_fmas_f32 v67, v191, v187, v189
	v_pk_fma_f32 v[70:71], v[132:133], v[70:71], v[28:29]
	v_pk_fma_f32 v[6:7], v[130:131], v[6:7], v[30:31]
	v_div_fixup_f32 v66, v84, v184, 1.0
	v_pk_fma_f32 v[72:73], v[130:131], v[72:73], v[30:31]
	v_cvt_pk_bf16_f32 v82, v4, v5
	v_cvt_pk_bf16_f32 v83, v6, v7
	v_div_fixup_f32 v84, v67, v185, 1.0
	v_sub_f32_e32 v85, v5, v71
	v_pk_fma_f32 v[8:9], v[136:137], v[8:9], v[20:21]
	v_pk_fma_f32 v[74:75], v[136:137], v[74:75], v[20:21]
	v_pk_mul_f32 v[56:57], v[56:57], v[66:67] op_sel_hi:[1,0]
	v_pk_mul_f32 v[58:59], v[58:59], v[66:67] op_sel_hi:[1,0]
	v_pk_mul_f32 v[60:61], v[60:61], v[66:67] op_sel_hi:[1,0]
	v_pk_mul_f32 v[62:63], v[62:63], v[66:67] op_sel_hi:[1,0]
	v_pk_mul_f32 v[52:53], v[52:53], v[66:67] op_sel_hi:[1,0]
	v_pk_mul_f32 v[54:55], v[54:55], v[66:67] op_sel_hi:[1,0]
	v_pk_mul_f32 v[48:49], v[48:49], v[66:67] op_sel_hi:[1,0]
	v_pk_mul_f32 v[50:51], v[50:51], v[66:67] op_sel_hi:[1,0]
	global_store_dwordx2 v[166:167], v[82:83], off sc1
	v_cvt_pk_bf16_f32 v66, v70, v71
	v_cvt_pk_bf16_f32 v67, v72, v73
	v_pk_add_f32 v[82:83], v[4:5], v[70:71]
	v_pk_add_f32 v[86:87], v[6:7], v[72:73]
	v_pk_mul_f32 v[44:45], v[44:45], v[84:85] op_sel_hi:[1,0]
	v_sub_f32_e32 v184, v4, v70
	v_sub_f32_e32 v185, v7, v73
	v_sub_f32_e32 v186, v6, v72
	v_pk_add_f32 v[70:71], v[8:9], v[74:75]
	global_store_dwordx2 v[168:169], v[66:67], off sc1
	v_cndmask_b32_e64 v66, v86, v6, s[4:5]
	v_cndmask_b32_e64 v67, v87, v7, s[4:5]
	v_cndmask_b32_e64 v82, v82, v4, s[4:5]
	v_cndmask_b32_e64 v83, v83, v5, s[4:5]
	v_pk_fma_f32 v[6:7], v[132:133], v[44:45], v[28:29]
	v_cvt_pk_bf16_f32 v44, v82, v83
	v_cvt_pk_bf16_f32 v45, v66, v67
	v_pk_fma_f32 v[10:11], v[134:135], v[10:11], v[22:23]
	v_pk_fma_f32 v[76:77], v[134:135], v[76:77], v[22:23]
	v_sub_f32_e32 v187, v9, v75
	v_sub_f32_e32 v188, v8, v74
	v_cndmask_b32_e64 v186, v186, 0, s[4:5]
	v_cndmask_b32_e64 v185, v185, 0, s[4:5]
	v_cndmask_b32_e64 v184, v184, 0, s[4:5]
	v_cndmask_b32_e64 v199, v85, 0, s[4:5]
	v_cndmask_b32_e64 v202, v70, v8, s[4:5]
	v_cndmask_b32_e64 v203, v71, v9, s[4:5]
	global_store_dwordx2 v[164:165], v[44:45], off sc1
	v_cvt_pk_bf16_f32 v44, v184, v199
	v_cvt_pk_bf16_f32 v45, v186, v185
	global_store_dwordx2 v[162:163], v[44:45], off sc1
	v_cvt_pk_bf16_f32 v8, v8, v9
	v_cvt_pk_bf16_f32 v9, v10, v11
	v_pk_add_f32 v[72:73], v[10:11], v[76:77]
	global_store_dwordx2 v[166:167], v[8:9], off offset:512 sc1
	v_cvt_pk_bf16_f32 v8, v74, v75
	v_cvt_pk_bf16_f32 v9, v76, v77
	v_sub_f32_e32 v189, v11, v77
	v_sub_f32_e32 v190, v10, v76
	v_cndmask_b32_e64 v200, v72, v10, s[4:5]
	v_cndmask_b32_e64 v201, v73, v11, s[4:5]
	global_store_dwordx2 v[168:169], v[8:9], off offset:512 sc1
	v_cvt_pk_bf16_f32 v8, v202, v203
	v_cvt_pk_bf16_f32 v9, v200, v201
	v_cndmask_b32_e64 v190, v190, 0, s[4:5]
	v_cndmask_b32_e64 v189, v189, 0, s[4:5]
	v_cndmask_b32_e64 v188, v188, 0, s[4:5]
	v_cndmask_b32_e64 v187, v187, 0, s[4:5]
	global_store_dwordx2 v[164:165], v[8:9], off offset:512 sc1
	v_cvt_pk_bf16_f32 v8, v188, v187
	v_cvt_pk_bf16_f32 v9, v190, v189
	v_pk_fma_f32 v[14:15], v[138:139], v[14:15], v[18:19]
	v_pk_fma_f32 v[12:13], v[140:141], v[12:13], v[16:17]
	v_pk_fma_f32 v[80:81], v[138:139], v[80:81], v[18:19]
	v_pk_fma_f32 v[78:79], v[140:141], v[78:79], v[16:17]
	global_store_dwordx2 v[162:163], v[8:9], off offset:512 sc1
	v_cvt_pk_bf16_f32 v8, v12, v13
	v_cvt_pk_bf16_f32 v9, v14, v15
	v_pk_add_f32 v[88:89], v[12:13], v[78:79]
	v_pk_add_f32 v[90:91], v[14:15], v[80:81]
	global_store_dwordx2 v[166:167], v[8:9], off offset:1024 sc1
	v_cvt_pk_bf16_f32 v8, v78, v79
	v_cvt_pk_bf16_f32 v9, v80, v81
	v_pk_fma_f32 v[0:1], v[142:143], v[0:1], v[26:27]
	v_pk_fma_f32 v[2:3], v[142:143], v[2:3], v[26:27]
	v_sub_f32_e32 v191, v13, v79
	v_sub_f32_e32 v192, v12, v78
	v_sub_f32_e32 v193, v15, v81
	v_sub_f32_e32 v194, v14, v80
	v_cndmask_b32_e64 v90, v90, v14, s[4:5]
	v_cndmask_b32_e64 v91, v91, v15, s[4:5]
	v_cndmask_b32_e64 v204, v88, v12, s[4:5]
	v_cndmask_b32_e64 v205, v89, v13, s[4:5]
	global_store_dwordx2 v[168:169], v[8:9], off offset:1024 sc1
	v_cvt_pk_bf16_f32 v8, v204, v205
	v_cvt_pk_bf16_f32 v9, v90, v91
	v_pk_fma_f32 v[68:69], v[144:145], v[68:69], v[24:25]
	v_pk_fma_f32 v[64:65], v[144:145], v[64:65], v[24:25]
	v_pk_add_f32 v[94:95], v[0:1], v[2:3]
	v_cndmask_b32_e64 v194, v194, 0, s[4:5]
	v_cndmask_b32_e64 v193, v193, 0, s[4:5]
	v_cndmask_b32_e64 v192, v192, 0, s[4:5]
	v_cndmask_b32_e64 v191, v191, 0, s[4:5]
	global_store_dwordx2 v[164:165], v[8:9], off offset:1024 sc1
	v_cvt_pk_bf16_f32 v8, v192, v191
	v_cvt_pk_bf16_f32 v9, v194, v193
	v_pk_add_f32 v[92:93], v[68:69], v[64:65]
	v_sub_f32_e32 v197, v1, v3
	v_sub_f32_e32 v198, v0, v2
	v_cndmask_b32_e64 v94, v94, v0, s[4:5]
	v_cndmask_b32_e64 v95, v95, v1, s[4:5]
	global_store_dwordx2 v[162:163], v[8:9], off offset:1024 sc1
	v_cvt_pk_bf16_f32 v8, v68, v69
	v_cvt_pk_bf16_f32 v9, v0, v1
	global_store_dwordx2 v[166:167], v[8:9], off offset:1536 sc1
; __device__ __forceinline__ unsigned cvt_pk_bf16(float lo, float hi) { unsigned r; asm volatile("v_cvt_pk_bf16_f32 %0, %1, %2" : "=v"(r) : "v"(lo), "v"(hi)); return r; }
; __device__ __forceinline__ void pass_h_fold(const float* src, const float* g, const float* mod, bf16_t* H, bf16_t* HE, bf16_t* HO) {
;     ...
;             for (int q = 0; q < 2; ++q) { const int s = sb + half * 2 + q, pr = (s == 0) ? SEQ / 2 : SEQ - s;
;                 const f32x4* x0 = (const f32x4*)(src + (size_t)(b * SEQ + s) * DM) + lane; const f32x4* x1 = (const f32x4*)(src + (size_t)(b * SEQ + pr) * DM) + lane;
; #pragma unroll
;                 for (int j = 0; j < 4; ++j) { v[q][0][j] = x0[64 * j]; v[q][1][j] = x1[64 * j]; } }
;     ...
;                 u32x2* o0 = (u32x2*)(H + (size_t)(b * SEQ + s) * DM) + lane; u32x2* o1 = (u32x2*)(H + (size_t)(b * SEQ + pr) * DM) + lane;
;                 u32x2* oe = (u32x2*)(HE + (size_t)(b * 1024 + s) * DM) + lane; u32x2* oo = (u32x2*)(HO + (size_t)(b * 1024 + s) * DM) + lane;
; #pragma unroll
;                 for (int j = 0; j < 4; ++j) { const f32x4 h0 = (v[q][0][j] * r0) * mul[j] + sh[j], h1 = (v[q][1][j] * r1) * mul[j] + sh[j];
;                     u32x2 w; w.x = cvt_pk_bf16(h0[0], h0[1]); w.y = cvt_pk_bf16(h0[2], h0[3]); o0[64 * j] = w;
;                     w.x = cvt_pk_bf16(h1[0], h1[1]); w.y = cvt_pk_bf16(h1[2], h1[3]); o1[64 * j] = w;
;                     const f32x4 e = (s == 0) ? h0 : h0 + h1, o = (s == 0) ? (f32x4){0.f, 0.f, 0.f, 0.f} : h0 - h1;
;                     w.x = cvt_pk_bf16(e[0], e[1]); w.y = cvt_pk_bf16(e[2], e[3]); oe[64 * j] = w;
;                     w.x = cvt_pk_bf16(o[0], o[1]); w.y = cvt_pk_bf16(o[2], o[3]); oo[64 * j] = w; } }
	v_cvt_pk_bf16_f32 v0, v64, v65
	v_cvt_pk_bf16_f32 v1, v2, v3
	v_sub_f32_e32 v195, v69, v65
	v_sub_f32_e32 v196, v68, v64
	v_cndmask_b32_e64 v92, v92, v68, s[4:5]
	v_cndmask_b32_e64 v93, v93, v69, s[4:5]
	global_store_dwordx2 v[168:169], v[0:1], off offset:1536 sc1
	v_cvt_pk_bf16_f32 v0, v92, v93
	v_cvt_pk_bf16_f32 v1, v94, v95
	v_cndmask_b32_e64 v198, v198, 0, s[4:5]
	v_cndmask_b32_e64 v197, v197, 0, s[4:5]
	v_cndmask_b32_e64 v196, v196, 0, s[4:5]
	v_cndmask_b32_e64 v195, v195, 0, s[4:5]
	global_store_dwordx2 v[164:165], v[0:1], off offset:1536 sc1
	v_cvt_pk_bf16_f32 v0, v196, v195
	v_cvt_pk_bf16_f32 v1, v198, v197
	v_pk_fma_f32 v[58:59], v[130:131], v[58:59], v[30:31]
	v_pk_fma_f32 v[56:57], v[132:133], v[56:57], v[28:29]
	v_pk_mul_f32 v[46:47], v[46:47], v[84:85] op_sel_hi:[1,0]
	global_store_dwordx2 v[162:163], v[0:1], off offset:1536 sc1
	v_cvt_pk_bf16_f32 v0, v56, v57
	v_cvt_pk_bf16_f32 v1, v58, v59
	v_pk_fma_f32 v[4:5], v[130:131], v[46:47], v[30:31]
	global_store_dwordx2 v[154:155], v[0:1], off sc1
	v_cvt_pk_bf16_f32 v0, v6, v7
	v_cvt_pk_bf16_f32 v1, v4, v5
	v_pk_add_f32 v[46:47], v[58:59], v[4:5]
	v_pk_add_f32 v[66:67], v[56:57], v[6:7]
	global_store_dwordx2 v[160:161], v[0:1], off sc1
	v_cvt_pk_bf16_f32 v0, v66, v67
	v_cvt_pk_bf16_f32 v1, v46, v47
	v_sub_f32_e32 v206, v58, v4
	v_sub_f32_e32 v207, v59, v5
	v_sub_f32_e32 v208, v56, v6
	v_sub_f32_e32 v209, v57, v7
	global_store_dwordx2 v[152:153], v[0:1], off sc1
	v_cvt_pk_bf16_f32 v0, v208, v209
	v_cvt_pk_bf16_f32 v1, v206, v207
	v_pk_fma_f32 v[62:63], v[134:135], v[62:63], v[22:23]
	v_pk_fma_f32 v[60:61], v[136:137], v[60:61], v[20:21]
	v_pk_mul_f32 v[40:41], v[40:41], v[84:85] op_sel_hi:[1,0]
	v_pk_mul_f32 v[42:43], v[42:43], v[84:85] op_sel_hi:[1,0]
	global_store_dwordx2 v[150:151], v[0:1], off sc1
	v_cvt_pk_bf16_f32 v0, v60, v61
	v_cvt_pk_bf16_f32 v1, v62, v63
	v_pk_fma_f32 v[42:43], v[134:135], v[42:43], v[22:23]
	v_pk_fma_f32 v[40:41], v[136:137], v[40:41], v[20:21]
	global_store_dwordx2 v[154:155], v[0:1], off offset:512 sc1
	v_cvt_pk_bf16_f32 v0, v40, v41
	v_cvt_pk_bf16_f32 v1, v42, v43
	v_pk_add_f32 v[70:71], v[62:63], v[42:43]
	v_pk_add_f32 v[72:73], v[60:61], v[40:41]
	global_store_dwordx2 v[160:161], v[0:1], off offset:512 sc1
	v_cvt_pk_bf16_f32 v0, v72, v73
	v_cvt_pk_bf16_f32 v1, v70, v71
	v_sub_f32_e32 v210, v62, v42
	v_sub_f32_e32 v211, v63, v43
	v_sub_f32_e32 v212, v60, v40
	v_sub_f32_e32 v213, v61, v41
	global_store_dwordx2 v[152:153], v[0:1], off offset:512 sc1
	v_cvt_pk_bf16_f32 v0, v212, v213
	v_cvt_pk_bf16_f32 v1, v210, v211
	v_pk_fma_f32 v[54:55], v[138:139], v[54:55], v[18:19]
	v_pk_fma_f32 v[52:53], v[140:141], v[52:53], v[16:17]
	v_pk_mul_f32 v[36:37], v[36:37], v[84:85] op_sel_hi:[1,0]
	v_pk_mul_f32 v[38:39], v[38:39], v[84:85] op_sel_hi:[1,0]
	global_store_dwordx2 v[150:151], v[0:1], off offset:512 sc1
	v_cvt_pk_bf16_f32 v0, v52, v53
	v_cvt_pk_bf16_f32 v1, v54, v55
	v_pk_fma_f32 v[38:39], v[138:139], v[38:39], v[18:19]
	v_pk_fma_f32 v[36:37], v[140:141], v[36:37], v[16:17]
	global_store_dwordx2 v[154:155], v[0:1], off offset:1024 sc1
	v_cvt_pk_bf16_f32 v0, v36, v37
	v_cvt_pk_bf16_f32 v1, v38, v39
	v_pk_mul_f32 v[32:33], v[32:33], v[84:85] op_sel_hi:[1,0]
	v_pk_mul_f32 v[34:35], v[34:35], v[84:85] op_sel_hi:[1,0]
	v_pk_add_f32 v[82:83], v[54:55], v[38:39]
	v_pk_add_f32 v[84:85], v[52:53], v[36:37]
	global_store_dwordx2 v[160:161], v[0:1], off offset:1024 sc1
	v_cvt_pk_bf16_f32 v0, v84, v85
	v_cvt_pk_bf16_f32 v1, v82, v83
	v_sub_f32_e32 v214, v54, v38
	v_sub_f32_e32 v215, v55, v39
	v_sub_f32_e32 v216, v52, v36
	v_sub_f32_e32 v217, v53, v37
	global_store_dwordx2 v[152:153], v[0:1], off offset:1024 sc1
	v_cvt_pk_bf16_f32 v0, v216, v217
	v_cvt_pk_bf16_f32 v1, v214, v215
	v_pk_fma_f32 v[50:51], v[142:143], v[50:51], v[26:27]
	v_pk_fma_f32 v[48:49], v[144:145], v[48:49], v[24:25]
	global_store_dwordx2 v[150:151], v[0:1], off offset:1024 sc1
	v_cvt_pk_bf16_f32 v0, v48, v49
	v_cvt_pk_bf16_f32 v1, v50, v51
	v_pk_fma_f32 v[34:35], v[142:143], v[34:35], v[26:27]
	v_pk_fma_f32 v[32:33], v[144:145], v[32:33], v[24:25]
	global_store_dwordx2 v[154:155], v[0:1], off offset:1536 sc1
	v_cvt_pk_bf16_f32 v0, v32, v33
	v_cvt_pk_bf16_f32 v1, v34, v35
	v_pk_add_f32 v[86:87], v[50:51], v[34:35]
	v_pk_add_f32 v[88:89], v[48:49], v[32:33]
	global_store_dwordx2 v[160:161], v[0:1], off offset:1536 sc1
	v_cvt_pk_bf16_f32 v0, v88, v89
	v_cvt_pk_bf16_f32 v1, v86, v87
	v_sub_f32_e32 v218, v50, v34
	v_sub_f32_e32 v219, v51, v35
	v_sub_f32_e32 v220, v48, v32
	v_sub_f32_e32 v221, v49, v33
	global_store_dwordx2 v[152:153], v[0:1], off offset:1536 sc1
	v_cvt_pk_bf16_f32 v0, v220, v221
	v_cvt_pk_bf16_f32 v1, v218, v219
	global_store_dwordx2 v[150:151], v[0:1], off offset:1536 sc1
	global_load_dwordx4 v[68:71], v[148:149], off
	global_load_dwordx4 v[60:63], v[158:159], off
	global_load_dwordx4 v[72:75], v[148:149], off offset:1024
	global_load_dwordx4 v[52:55], v[158:159], off offset:1024
	global_load_dwordx4 v[64:67], v[148:149], off offset:3072
	global_load_dwordx4 v[76:79], v[148:149], off offset:2048
	global_load_dwordx4 v[48:51], v[158:159], off offset:3072
	global_load_dwordx4 v[56:59], v[158:159], off offset:2048
	global_load_dwordx4 v[32:35], v[146:147], off
	global_load_dwordx4 v[4:7], v[156:157], off
	global_load_dwordx4 v[40:43], v[146:147], off offset:1024
	global_load_dwordx4 v[8:11], v[156:157], off offset:1024
	global_load_dwordx4 v[36:39], v[146:147], off offset:3072
	global_load_dwordx4 v[44:47], v[146:147], off offset:2048
	global_load_dwordx4 v[0:3], v[156:157], off offset:3072
	global_load_dwordx4 v[12:15], v[156:157], off offset:2048
	s_waitcnt vmcnt(15)
; __device__ __forceinline__ void pass_h_fold(const float* src, const float* g, const float* mod, bf16_t* H, bf16_t* HE, bf16_t* HO) {
;     ...
;                 float t0 = 0.f, t1 = 0.f;
; #pragma unroll
;                 for (int j = 0; j < 4; ++j) { const f32x4 a = v[q][0][j], c = v[q][1][j]; t0 += (a[0] * a[0] + a[1] * a[1]) + (a[2] * a[2] + a[3] * a[3]); t1 += (c[0] * c[0] + c[1] * c[1]) + (c[2] * c[2] + c[3] * c[3]); }
;                 t0 = wave_sum(t0); t1 = wave_sum(t1);
	v_pk_mul_f32 v[80:81], v[70:71], v[70:71]
	v_pk_mul_f32 v[82:83], v[68:69], v[68:69]
	s_waitcnt vmcnt(14)
	v_pk_mul_f32 v[84:85], v[62:63], v[62:63]
	v_pk_mul_f32 v[86:87], v[60:61], v[60:61]
	s_waitcnt vmcnt(13)
	v_pk_mul_f32 v[88:89], v[74:75], v[74:75]
	v_pk_mul_f32 v[90:91], v[72:73], v[72:73]
	s_waitcnt vmcnt(12)
	v_pk_mul_f32 v[92:93], v[54:55], v[54:55]
	v_pk_mul_f32 v[94:95], v[52:53], v[52:53]
	s_waitcnt vmcnt(10)
	v_mul_f32_e32 v146, v77, v77
	v_mul_f32_e32 v148, v79, v79
	s_waitcnt vmcnt(8)
	v_mul_f32_e32 v150, v57, v57
	v_mul_f32_e32 v152, v59, v59
	s_waitcnt vmcnt(7)
	v_pk_mul_f32 v[154:155], v[34:35], v[34:35]
	v_pk_mul_f32 v[156:157], v[32:33], v[32:33]
	s_waitcnt vmcnt(6)
	v_pk_mul_f32 v[158:159], v[6:7], v[6:7]
	v_pk_mul_f32 v[160:161], v[4:5], v[4:5]
	s_waitcnt vmcnt(5)
	v_pk_mul_f32 v[162:163], v[42:43], v[42:43]
	v_pk_mul_f32 v[164:165], v[40:41], v[40:41]
	v_pk_mov_b32 v[192:193], v[82:83], v[80:81] op_sel:[1,0]
	v_mov_b32_e32 v83, v81
	v_pk_mov_b32 v[80:81], v[86:87], v[84:85] op_sel:[1,0]
	v_mov_b32_e32 v87, v85
	v_pk_mov_b32 v[84:85], v[90:91], v[88:89] op_sel:[1,0]
	v_mov_b32_e32 v91, v89
	s_waitcnt vmcnt(4)
	v_pk_mul_f32 v[166:167], v[10:11], v[10:11]
	v_pk_mul_f32 v[168:169], v[8:9], v[8:9]
	v_pk_mov_b32 v[88:89], v[94:95], v[92:93] op_sel:[1,0]
	v_mov_b32_e32 v95, v93
	v_pk_fma_f32 v[92:93], v[76:77], v[76:77], v[146:147] op_sel_hi:[1,1,0]
	v_pk_fma_f32 v[146:147], v[78:79], v[78:79], v[148:149] op_sel_hi:[1,1,0]
	v_pk_fma_f32 v[148:149], v[56:57], v[56:57], v[150:151] op_sel_hi:[1,1,0]
	v_pk_fma_f32 v[150:151], v[58:59], v[58:59], v[152:153] op_sel_hi:[1,1,0]
	v_pk_mov_b32 v[152:153], v[156:157], v[154:155] op_sel:[1,0]
	v_mov_b32_e32 v157, v155
	v_pk_mov_b32 v[154:155], v[160:161], v[158:159] op_sel:[1,0]
	v_mov_b32_e32 v161, v159
	v_pk_mov_b32 v[158:159], v[164:165], v[162:163] op_sel:[1,0]
	v_mov_b32_e32 v165, v163
	v_pk_add_f32 v[82:83], v[192:193], v[82:83]
	v_pk_add_f32 v[84:85], v[84:85], v[90:91]
	v_mul_f32_e32 v191, v64, v64
	v_mul_f32_e32 v194, v65, v65
	v_mul_f32_e32 v195, v66, v66
	v_mul_f32_e32 v196, v67, v67
	v_mul_f32_e32 v199, v50, v50
	v_mul_f32_e32 v200, v51, v51
	s_waitcnt vmcnt(2)
	v_mul_f32_e32 v184, v45, v45
	v_mul_f32_e32 v186, v47, v47
	v_pk_mov_b32 v[162:163], v[168:169], v[166:167] op_sel:[1,0]
	v_mov_b32_e32 v169, v167
	v_pk_add_f32 v[80:81], v[80:81], v[86:87]
	v_pk_add_f32 v[86:87], v[88:89], v[94:95]
	v_pk_add_f32 v[88:89], v[152:153], v[156:157]
	v_pk_add_f32 v[94:95], v[158:159], v[164:165]
	v_pk_add_f32 v[82:83], v[82:83], v[82:83] op_sel:[0,1] op_sel_hi:[1,0]
	v_pk_add_f32 v[84:85], v[84:85], v[84:85] op_sel:[0,1] op_sel_hi:[1,0]
	v_mul_f32_e32 v197, v48, v48
	v_mul_f32_e32 v198, v49, v49
	v_mul_f32_e32 v201, v36, v36
	v_mul_f32_e32 v202, v37, v37
	v_mul_f32_e32 v203, v38, v38
	v_mul_f32_e32 v204, v39, v39
	s_waitcnt vmcnt(0)
	v_mul_f32_e32 v188, v13, v13
	v_mul_f32_e32 v190, v15, v15
	v_pk_fma_f32 v[166:167], v[44:45], v[44:45], v[184:185] op_sel_hi:[1,1,0]
	v_pk_fma_f32 v[184:185], v[46:47], v[46:47], v[186:187] op_sel_hi:[1,1,0]
	v_mov_b32_e32 v93, v195
	v_mov_b32_e32 v147, v196
	v_mov_b32_e32 v149, v199
	v_mov_b32_e32 v151, v200
	v_pk_add_f32 v[90:91], v[154:155], v[160:161]
	v_pk_add_f32 v[152:153], v[162:163], v[168:169]
	v_pk_add_f32 v[80:81], v[80:81], v[80:81] op_sel:[0,1] op_sel_hi:[1,0]
	v_pk_add_f32 v[86:87], v[86:87], v[86:87] op_sel:[0,1] op_sel_hi:[1,0]
	v_pk_add_f32 v[88:89], v[88:89], v[88:89] op_sel:[0,1] op_sel_hi:[1,0]
	v_pk_add_f32 v[94:95], v[94:95], v[94:95] op_sel:[0,1] op_sel_hi:[1,0]
	v_mov_b32_e32 v83, v191
	v_mov_b32_e32 v85, v194
	v_mul_f32_e32 v205, v0, v0
	v_mul_f32_e32 v206, v1, v1
	v_mul_f32_e32 v207, v2, v2
	v_mul_f32_e32 v208, v3, v3
	v_pk_fma_f32 v[186:187], v[12:13], v[12:13], v[188:189] op_sel_hi:[1,1,0]
	v_pk_fma_f32 v[188:189], v[14:15], v[14:15], v[190:191] op_sel_hi:[1,1,0]
	v_mov_b32_e32 v167, v203
	v_mov_b32_e32 v185, v204
	v_pk_add_f32 v[92:93], v[92:93], v[146:147]
	v_pk_add_f32 v[146:147], v[148:149], v[150:151]
	v_pk_add_f32 v[90:91], v[90:91], v[90:91] op_sel:[0,1] op_sel_hi:[1,0]
	v_pk_add_f32 v[150:151], v[152:153], v[152:153] op_sel:[0,1] op_sel_hi:[1,0]
	v_mov_b32_e32 v81, v197
	v_mov_b32_e32 v87, v198
	v_mov_b32_e32 v89, v201
	v_mov_b32_e32 v95, v202
	v_pk_add_f32 v[82:83], v[82:83], v[84:85]
	v_mov_b32_e32 v187, v207
	v_mov_b32_e32 v189, v208
	v_pk_add_f32 v[148:149], v[166:167], v[184:185]
	v_mov_b32_e32 v91, v205
	v_mov_b32_e32 v151, v206
	v_pk_add_f32 v[80:81], v[80:81], v[86:87]
	v_pk_add_f32 v[84:85], v[88:89], v[94:95]
	v_pk_add_f32 v[82:83], v[82:83], v[92:93]
	v_pk_add_f32 v[152:153], v[186:187], v[188:189]
	v_pk_add_f32 v[86:87], v[90:91], v[150:151]
	v_pk_add_f32 v[80:81], v[80:81], v[146:147]
	v_pk_add_f32 v[84:85], v[84:85], v[148:149]
	v_add_f32_e32 v82, v82, v83
	v_pk_add_f32 v[86:87], v[86:87], v[152:153]
	v_add_f32_e32 v80, v80, v81
	v_add_f32_e32 v81, v84, v85
	ds_bpermute_b32 v84, v174, v82
	v_add_f32_e32 v83, v86, v87
	ds_bpermute_b32 v85, v174, v80
	ds_bpermute_b32 v86, v174, v81
	ds_bpermute_b32 v87, v174, v83
	s_waitcnt lgkmcnt(3)
	v_add_f32_e32 v82, v82, v84
	ds_bpermute_b32 v84, v175, v82
	s_waitcnt lgkmcnt(3)
	v_add_f32_e32 v80, v80, v85
	s_waitcnt lgkmcnt(2)
	v_add_f32_e32 v81, v81, v86
	ds_bpermute_b32 v85, v175, v80
	ds_bpermute_b32 v86, v175, v81
	s_waitcnt lgkmcnt(3)
	v_add_f32_e32 v83, v83, v87
	ds_bpermute_b32 v87, v175, v83
	s_waitcnt lgkmcnt(3)
	v_add_f32_e32 v82, v82, v84
	s_waitcnt lgkmcnt(2)
	v_add_f32_e32 v80, v80, v85
	s_waitcnt lgkmcnt(1)
	v_add_f32_e32 v81, v81, v86
	ds_bpermute_b32 v84, v176, v82
	ds_bpermute_b32 v85, v176, v80
	ds_bpermute_b32 v86, v176, v81
	s_waitcnt lgkmcnt(3)
; __device__ __forceinline__ float wave_sum(float v) {
; #pragma unroll
;     for (int o = 1; o < 64; o <<= 1) v += __shfl_xor(v, o);
;     return v;
; __device__ __forceinline__ void pass_h_fold(const float* src, const float* g, const float* mod, bf16_t* H, bf16_t* HE, bf16_t* HO) {
;     ...
;                 t0 = wave_sum(t0); t1 = wave_sum(t1);
;                 const float r0 = 1.0f / sqrtf(t0 * (1.0f / DM) + EPS), r1 = 1.0f / sqrtf(t1 * (1.0f / DM) + EPS);
	v_add_f32_e32 v83, v83, v87
	ds_bpermute_b32 v87, v176, v83
	s_waitcnt lgkmcnt(3)
	v_add_f32_e32 v82, v82, v84
	s_waitcnt lgkmcnt(2)
	v_add_f32_e32 v80, v80, v85
	s_waitcnt lgkmcnt(1)
	v_add_f32_e32 v81, v81, v86
	ds_bpermute_b32 v84, v177, v82
	ds_bpermute_b32 v85, v177, v80
	ds_bpermute_b32 v86, v177, v81
	s_waitcnt lgkmcnt(3)
	v_add_f32_e32 v83, v83, v87
	ds_bpermute_b32 v87, v177, v83
	s_waitcnt lgkmcnt(3)
	v_add_f32_e32 v82, v82, v84
	s_waitcnt lgkmcnt(2)
	v_add_f32_e32 v80, v80, v85
	s_waitcnt lgkmcnt(1)
	v_add_f32_e32 v81, v81, v86
	ds_bpermute_b32 v84, v178, v82
	ds_bpermute_b32 v85, v178, v80
	ds_bpermute_b32 v86, v178, v81
	s_waitcnt lgkmcnt(3)
	v_add_f32_e32 v83, v83, v87
	ds_bpermute_b32 v87, v178, v83
	s_waitcnt lgkmcnt(3)
	v_add_f32_e32 v82, v82, v84
	s_waitcnt lgkmcnt(2)
	v_add_f32_e32 v80, v80, v85
	s_waitcnt lgkmcnt(1)
	v_add_f32_e32 v81, v81, v86
	ds_bpermute_b32 v84, v179, v82
	ds_bpermute_b32 v85, v179, v80
	ds_bpermute_b32 v86, v179, v81
	s_waitcnt lgkmcnt(3)
	v_add_f32_e32 v83, v83, v87
	ds_bpermute_b32 v87, v179, v83
	s_waitcnt lgkmcnt(3)
	v_add_f32_e32 v82, v82, v84
	s_waitcnt lgkmcnt(2)
	v_add_f32_e32 v80, v80, v85
	s_waitcnt lgkmcnt(1)
	v_add_f32_e32 v81, v81, v86
	v_fmamk_f32 v82, v82, 0x3a800000, v182
	v_fmamk_f32 v80, v80, 0x3a800000, v182
	v_fmamk_f32 v81, v81, 0x3a800000, v182
	v_mul_f32_e32 v84, 0x4f800000, v82
	v_cmp_gt_f32_e64 s[8:9], s40, v82
	v_mul_f32_e32 v85, 0x4f800000, v80
	v_cmp_gt_f32_e32 vcc, s40, v80
	v_mul_f32_e32 v86, 0x4f800000, v81
	v_cmp_gt_f32_e64 s[4:5], s40, v81
	v_cndmask_b32_e64 v82, v82, v84, s[8:9]
	s_waitcnt lgkmcnt(0)
	v_add_f32_e32 v83, v83, v87
	v_cndmask_b32_e32 v80, v80, v85, vcc
	v_cndmask_b32_e64 v81, v81, v86, s[4:5]
	v_sqrt_f32_e32 v84, v82
	v_fmamk_f32 v83, v83, 0x3a800000, v182
	v_sqrt_f32_e32 v85, v80
	v_sqrt_f32_e32 v86, v81
	v_mul_f32_e32 v87, 0x4f800000, v83
	v_cmp_gt_f32_e64 s[6:7], s40, v83
	v_add_u32_e32 v88, -1, v84
	v_add_u32_e32 v89, 1, v84
	v_cndmask_b32_e64 v83, v83, v87, s[6:7]
	v_sqrt_f32_e32 v87, v83
	v_add_u32_e32 v90, -1, v85
	v_add_u32_e32 v92, -1, v86
	v_fma_f32 v146, -v88, v84, v82
	v_add_u32_e32 v91, 1, v85
	v_add_u32_e32 v93, 1, v86
	v_fma_f32 v147, -v89, v84, v82
	v_fma_f32 v148, -v90, v85, v80
	v_fma_f32 v150, -v92, v86, v81
	v_cmp_ge_f32_e64 s[12:13], 0, v146
	v_fma_f32 v149, -v91, v85, v80
	v_fma_f32 v151, -v93, v86, v81
	v_cndmask_b32_e64 v84, v84, v88, s[12:13]
	v_cmp_ge_f32_e64 s[12:13], 0, v148
	v_cmp_ge_f32_e64 s[14:15], 0, v150
	v_cmp_lt_f32_e64 s[18:19], 0, v147
	v_add_u32_e32 v94, -1, v87
	v_cndmask_b32_e64 v85, v85, v90, s[12:13]
	v_cmp_lt_f32_e64 s[12:13], 0, v149
	v_cndmask_b32_e64 v86, v86, v92, s[14:15]
	v_cmp_lt_f32_e64 s[14:15], 0, v151
	v_cndmask_b32_e64 v84, v84, v89, s[18:19]
	v_add_u32_e32 v95, 1, v87
	v_fma_f32 v152, -v94, v87, v83
	v_cndmask_b32_e64 v85, v85, v91, s[12:13]
	v_cndmask_b32_e64 v86, v86, v93, s[14:15]
	v_mul_f32_e32 v88, 0x37800000, v84
	v_fma_f32 v153, -v95, v87, v83
	v_cmp_ge_f32_e64 s[16:17], 0, v152
	v_mul_f32_e32 v89, 0x37800000, v85
	v_mul_f32_e32 v90, 0x37800000, v86
	v_cndmask_b32_e64 v84, v84, v88, s[8:9]
	v_cmp_class_f32_e64 s[8:9], v82, v183
	v_cndmask_b32_e64 v87, v87, v94, s[16:17]
	v_cmp_lt_f32_e64 s[16:17], 0, v153
	v_cndmask_b32_e32 v85, v85, v89, vcc
	v_cmp_class_f32_e32 vcc, v80, v183
	v_cndmask_b32_e64 v86, v86, v90, s[4:5]
	v_cmp_class_f32_e64 s[4:5], v81, v183
	v_cndmask_b32_e64 v82, v84, v82, s[8:9]
	v_cndmask_b32_e64 v87, v87, v95, s[16:17]
	v_cndmask_b32_e32 v84, v85, v80, vcc
	v_cndmask_b32_e64 v81, v86, v81, s[4:5]
	v_div_scale_f32 v80, s[4:5], v82, v82, 1.0
	v_mul_f32_e32 v91, 0x37800000, v87
	v_div_scale_f32 v86, s[4:5], v84, v84, 1.0
	v_rcp_f32_e32 v92, v80
	v_cndmask_b32_e64 v87, v87, v91, s[6:7]
	v_cmp_class_f32_e64 s[6:7], v83, v183
	v_rcp_f32_e32 v93, v86
	v_fma_f32 v146, -v80, v92, 1.0
	v_cndmask_b32_e64 v85, v87, v83, s[6:7]
	v_div_scale_f32 v88, s[6:7], v81, v81, 1.0
	v_div_scale_f32 v90, s[8:9], v85, v85, 1.0
	v_rcp_f32_e32 v94, v88
	v_rcp_f32_e32 v95, v90
	v_div_scale_f32 v83, vcc, 1.0, v82, 1.0
	v_fma_f32 v147, -v86, v93, 1.0
	v_fmac_f32_e32 v92, v146, v92
	v_div_scale_f32 v87, s[4:5], 1.0, v84, 1.0
	v_fmac_f32_e32 v93, v147, v93
	v_mul_f32_e32 v146, v83, v92
	v_fma_f32 v148, -v88, v94, 1.0
	v_mul_f32_e32 v147, v87, v93
	v_fma_f32 v150, -v80, v146, v83
	v_div_scale_f32 v89, s[6:7], 1.0, v81, 1.0
	v_fma_f32 v149, -v90, v95, 1.0
	v_fmac_f32_e32 v94, v148, v94
	v_fma_f32 v151, -v86, v147, v87
	v_fmac_f32_e32 v146, v150, v92
	v_div_scale_f32 v91, s[8:9], 1.0, v85, 1.0
	v_fmac_f32_e32 v95, v149, v95
	v_mul_f32_e32 v148, v89, v94
	v_fmac_f32_e32 v147, v151, v93
	v_fma_f32 v80, -v80, v146, v83
	v_mul_f32_e32 v149, v91, v95
	v_fma_f32 v152, -v88, v148, v89
	v_fma_f32 v83, -v86, v147, v87
	v_div_fmas_f32 v80, v80, v92, v146
	s_mov_b64 vcc, s[4:5]
	v_fma_f32 v153, -v90, v149, v91
	v_fmac_f32_e32 v148, v152, v94
	v_div_fixup_f32 v80, v80, v82, 1.0
	v_div_fmas_f32 v82, v83, v93, v147
	v_fmac_f32_e32 v149, v153, v95
	v_fma_f32 v86, -v88, v148, v89
	v_div_fixup_f32 v82, v82, v84, 1.0
	s_mov_b64 vcc, s[6:7]
	v_fma_f32 v87, -v90, v149, v91
	v_pk_mul_f32 v[68:69], v[68:69], v[80:81] op_sel_hi:[1,0]
	v_pk_mul_f32 v[70:71], v[70:71], v[80:81] op_sel_hi:[1,0]
	v_pk_mul_f32 v[72:73], v[72:73], v[80:81] op_sel_hi:[1,0]
	v_pk_mul_f32 v[74:75], v[74:75], v[80:81] op_sel_hi:[1,0]
	v_pk_mul_f32 v[76:77], v[76:77], v[80:81] op_sel_hi:[1,0]
	v_pk_mul_f32 v[78:79], v[78:79], v[80:81] op_sel_hi:[1,0]
	v_pk_mul_f32 v[64:65], v[64:65], v[80:81] op_sel_hi:[1,0]
	v_pk_mul_f32 v[66:67], v[66:67], v[80:81] op_sel_hi:[1,0]
	v_div_fmas_f32 v80, v86, v94, v148
	v_pk_mul_f32 v[62:63], v[62:63], v[82:83] op_sel_hi:[1,0]
; __device__ __forceinline__ unsigned cvt_pk_bf16(float lo, float hi) { unsigned r; asm volatile("v_cvt_pk_bf16_f32 %0, %1, %2" : "=v"(r) : "v"(lo), "v"(hi)); return r; }
; __device__ __forceinline__ void pass_h_fold(const float* src, const float* g, const float* mod, bf16_t* H, bf16_t* HE, bf16_t* HO) {
;     ...
;                 u32x2* o0 = (u32x2*)(H + (size_t)(b * SEQ + s) * DM) + lane; u32x2* o1 = (u32x2*)(H + (size_t)(b * SEQ + pr) * DM) + lane;
;                 u32x2* oe = (u32x2*)(HE + (size_t)(b * 1024 + s) * DM) + lane; u32x2* oo = (u32x2*)(HO + (size_t)(b * 1024 + s) * DM) + lane;
; #pragma unroll
;                 for (int j = 0; j < 4; ++j) { const f32x4 h0 = (v[q][0][j] * r0) * mul[j] + sh[j], h1 = (v[q][1][j] * r1) * mul[j] + sh[j];
;                     u32x2 w; w.x = cvt_pk_bf16(h0[0], h0[1]); w.y = cvt_pk_bf16(h0[2], h0[3]); o0[64 * j] = w;
;                     w.x = cvt_pk_bf16(h1[0], h1[1]); w.y = cvt_pk_bf16(h1[2], h1[3]); o1[64 * j] = w;
;                     const f32x4 e = (s == 0) ? h0 : h0 + h1, o = (s == 0) ? (f32x4){0.f, 0.f, 0.f, 0.f} : h0 - h1;
;                     w.x = cvt_pk_bf16(e[0], e[1]); w.y = cvt_pk_bf16(e[2], e[3]); oe[64 * j] = w;
;                     w.x = cvt_pk_bf16(o[0], o[1]); w.y = cvt_pk_bf16(o[2], o[3]); oo[64 * j] = w; } }
	s_mov_b64 vcc, s[8:9]
	v_pk_fma_f32 v[70:71], v[130:131], v[70:71], v[30:31]
	v_div_fixup_f32 v80, v80, v81, 1.0
	v_div_fmas_f32 v81, v87, v95, v149
	v_pk_fma_f32 v[62:63], v[130:131], v[62:63], v[30:31]
	v_pk_mul_f32 v[60:61], v[60:61], v[82:83] op_sel_hi:[1,0]
	v_div_fixup_f32 v84, v81, v85, 1.0
	v_sub_f32_e32 v85, v70, v62
	v_pk_fma_f32 v[68:69], v[132:133], v[68:69], v[28:29]
	v_pk_mul_f32 v[52:53], v[52:53], v[82:83] op_sel_hi:[1,0]
	v_pk_mul_f32 v[54:55], v[54:55], v[82:83] op_sel_hi:[1,0]
	v_pk_mul_f32 v[56:57], v[56:57], v[82:83] op_sel_hi:[1,0]
	v_pk_mul_f32 v[58:59], v[58:59], v[82:83] op_sel_hi:[1,0]
	v_pk_mul_f32 v[48:49], v[48:49], v[82:83] op_sel_hi:[1,0]
	v_pk_mul_f32 v[50:51], v[50:51], v[82:83] op_sel_hi:[1,0]
	v_pk_fma_f32 v[60:61], v[132:133], v[60:61], v[28:29]
	v_cvt_pk_bf16_f32 v82, v68, v69
	v_cvt_pk_bf16_f32 v83, v70, v71
	v_pk_mul_f32 v[32:33], v[32:33], v[80:81] op_sel_hi:[1,0]
	v_pk_mul_f32 v[34:35], v[34:35], v[80:81] op_sel_hi:[1,0]
	v_pk_mul_f32 v[40:41], v[40:41], v[80:81] op_sel_hi:[1,0]
	v_pk_mul_f32 v[42:43], v[42:43], v[80:81] op_sel_hi:[1,0]
	v_pk_mul_f32 v[44:45], v[44:45], v[80:81] op_sel_hi:[1,0]
	v_pk_mul_f32 v[46:47], v[46:47], v[80:81] op_sel_hi:[1,0]
	v_pk_mul_f32 v[36:37], v[36:37], v[80:81] op_sel_hi:[1,0]
	v_pk_mul_f32 v[38:39], v[38:39], v[80:81] op_sel_hi:[1,0]
	global_store_dwordx2 v[126:127], v[82:83], off sc1
	v_cvt_pk_bf16_f32 v80, v60, v61
	v_cvt_pk_bf16_f32 v81, v62, v63
	v_pk_mul_f32 v[12:13], v[12:13], v[84:85] op_sel_hi:[1,0]
	v_pk_fma_f32 v[76:77], v[140:141], v[76:77], v[16:17]
	v_pk_fma_f32 v[56:57], v[140:141], v[56:57], v[16:17]
	v_pk_add_f32 v[82:83], v[70:71], v[62:63]
	v_pk_add_f32 v[86:87], v[68:69], v[60:61]
	v_sub_f32_e32 v92, v71, v63
	v_sub_f32_e32 v93, v68, v60
	v_sub_f32_e32 v94, v69, v61
	v_pk_fma_f32 v[44:45], v[140:141], v[44:45], v[16:17]
	global_store_dwordx2 v[128:129], v[80:81], off sc1
	v_cvt_pk_bf16_f32 v80, v86, v87
	v_cvt_pk_bf16_f32 v81, v82, v83
	v_pk_fma_f32 v[12:13], v[140:141], v[12:13], v[16:17]
	global_store_dwordx2 v[124:125], v[80:81], off sc1
	v_cvt_pk_bf16_f32 v16, v93, v94
	v_cvt_pk_bf16_f32 v17, v85, v92
	v_pk_fma_f32 v[74:75], v[134:135], v[74:75], v[22:23]
	v_pk_fma_f32 v[72:73], v[136:137], v[72:73], v[20:21]
	global_store_dwordx2 v[122:123], v[16:17], off sc1
	v_cvt_pk_bf16_f32 v16, v72, v73
	v_cvt_pk_bf16_f32 v17, v74, v75
	v_pk_fma_f32 v[54:55], v[134:135], v[54:55], v[22:23]
	v_pk_fma_f32 v[52:53], v[136:137], v[52:53], v[20:21]
	global_store_dwordx2 v[126:127], v[16:17], off offset:512 sc1
	v_cvt_pk_bf16_f32 v16, v52, v53
	v_cvt_pk_bf16_f32 v17, v54, v55
	v_pk_add_f32 v[60:61], v[74:75], v[54:55]
	v_pk_add_f32 v[62:63], v[72:73], v[52:53]
	global_store_dwordx2 v[128:129], v[16:17], off offset:512 sc1
	v_cvt_pk_bf16_f32 v16, v62, v63
	v_cvt_pk_bf16_f32 v17, v60, v61
	v_sub_f32_e32 v95, v74, v54
	v_sub_f32_e32 v146, v75, v55
	v_sub_f32_e32 v147, v72, v52
	v_sub_f32_e32 v148, v73, v53
	global_store_dwordx2 v[124:125], v[16:17], off offset:512 sc1
	v_cvt_pk_bf16_f32 v16, v147, v148
	v_cvt_pk_bf16_f32 v17, v95, v146
	v_pk_fma_f32 v[78:79], v[138:139], v[78:79], v[18:19]
	global_store_dwordx2 v[122:123], v[16:17], off offset:512 sc1
	v_cvt_pk_bf16_f32 v16, v76, v77
	v_cvt_pk_bf16_f32 v17, v78, v79
	v_pk_fma_f32 v[58:59], v[138:139], v[58:59], v[18:19]
	global_store_dwordx2 v[126:127], v[16:17], off offset:1024 sc1
	v_cvt_pk_bf16_f32 v16, v56, v57
	v_cvt_pk_bf16_f32 v17, v58, v59
	v_pk_add_f32 v[68:69], v[78:79], v[58:59]
	v_pk_add_f32 v[70:71], v[76:77], v[56:57]
	global_store_dwordx2 v[128:129], v[16:17], off offset:1024 sc1
	v_cvt_pk_bf16_f32 v16, v70, v71
	v_cvt_pk_bf16_f32 v17, v68, v69
	v_sub_f32_e32 v149, v78, v58
	v_sub_f32_e32 v150, v79, v59
	v_sub_f32_e32 v151, v76, v56
	v_sub_f32_e32 v152, v77, v57
	global_store_dwordx2 v[124:125], v[16:17], off offset:1024 sc1
	v_cvt_pk_bf16_f32 v16, v151, v152
	v_cvt_pk_bf16_f32 v17, v149, v150
	v_pk_fma_f32 v[66:67], v[142:143], v[66:67], v[26:27]
	v_pk_fma_f32 v[64:65], v[144:145], v[64:65], v[24:25]
	global_store_dwordx2 v[122:123], v[16:17], off offset:1024 sc1
	v_cvt_pk_bf16_f32 v16, v64, v65
	v_cvt_pk_bf16_f32 v17, v66, v67
	v_pk_fma_f32 v[50:51], v[142:143], v[50:51], v[26:27]
	v_pk_fma_f32 v[48:49], v[144:145], v[48:49], v[24:25]
	global_store_dwordx2 v[126:127], v[16:17], off offset:1536 sc1
	v_cvt_pk_bf16_f32 v16, v48, v49
	v_cvt_pk_bf16_f32 v17, v50, v51
	v_pk_add_f32 v[88:89], v[66:67], v[50:51]
; __device__ __forceinline__ unsigned cvt_pk_bf16(float lo, float hi) { unsigned r; asm volatile("v_cvt_pk_bf16_f32 %0, %1, %2" : "=v"(r) : "v"(lo), "v"(hi)); return r; }
; __device__ __forceinline__ void pass_h_fold(const float* src, const float* g, const float* mod, bf16_t* H, bf16_t* HE, bf16_t* HO) {
;     ...
;                 u32x2* o0 = (u32x2*)(H + (size_t)(b * SEQ + s) * DM) + lane; u32x2* o1 = (u32x2*)(H + (size_t)(b * SEQ + pr) * DM) + lane;
;                 u32x2* oe = (u32x2*)(HE + (size_t)(b * 1024 + s) * DM) + lane; u32x2* oo = (u32x2*)(HO + (size_t)(b * 1024 + s) * DM) + lane;
; #pragma unroll
;                 for (int j = 0; j < 4; ++j) { const f32x4 h0 = (v[q][0][j] * r0) * mul[j] + sh[j], h1 = (v[q][1][j] * r1) * mul[j] + sh[j];
;                     u32x2 w; w.x = cvt_pk_bf16(h0[0], h0[1]); w.y = cvt_pk_bf16(h0[2], h0[3]); o0[64 * j] = w;
;                     w.x = cvt_pk_bf16(h1[0], h1[1]); w.y = cvt_pk_bf16(h1[2], h1[3]); o1[64 * j] = w;
;                     const f32x4 e = (s == 0) ? h0 : h0 + h1, o = (s == 0) ? (f32x4){0.f, 0.f, 0.f, 0.f} : h0 - h1;
;                     w.x = cvt_pk_bf16(e[0], e[1]); w.y = cvt_pk_bf16(e[2], e[3]); oe[64 * j] = w;
;                     w.x = cvt_pk_bf16(o[0], o[1]); w.y = cvt_pk_bf16(o[2], o[3]); oo[64 * j] = w; } }
	v_pk_add_f32 v[90:91], v[64:65], v[48:49]
	v_pk_mul_f32 v[4:5], v[4:5], v[84:85] op_sel_hi:[1,0]
	global_store_dwordx2 v[128:129], v[16:17], off offset:1536 sc1
	v_cvt_pk_bf16_f32 v16, v90, v91
	v_cvt_pk_bf16_f32 v17, v88, v89
	v_sub_f32_e32 v153, v66, v50
	v_sub_f32_e32 v154, v67, v51
	v_sub_f32_e32 v155, v64, v48
	v_sub_f32_e32 v156, v65, v49
	v_pk_fma_f32 v[32:33], v[132:133], v[32:33], v[28:29]
	v_pk_mul_f32 v[6:7], v[6:7], v[84:85] op_sel_hi:[1,0]
	v_pk_mul_f32 v[8:9], v[8:9], v[84:85] op_sel_hi:[1,0]
	v_pk_fma_f32 v[4:5], v[132:133], v[4:5], v[28:29]
	global_store_dwordx2 v[124:125], v[16:17], off offset:1536 sc1
	v_cvt_pk_bf16_f32 v16, v155, v156
	v_cvt_pk_bf16_f32 v17, v153, v154
	v_pk_fma_f32 v[34:35], v[130:131], v[34:35], v[30:31]
	v_pk_fma_f32 v[40:41], v[136:137], v[40:41], v[20:21]
	v_pk_mul_f32 v[10:11], v[10:11], v[84:85] op_sel_hi:[1,0]
	v_pk_mul_f32 v[14:15], v[14:15], v[84:85] op_sel_hi:[1,0]
	v_pk_mul_f32 v[0:1], v[0:1], v[84:85] op_sel_hi:[1,0]
	v_pk_mul_f32 v[2:3], v[2:3], v[84:85] op_sel_hi:[1,0]
	v_pk_fma_f32 v[6:7], v[130:131], v[6:7], v[30:31]
	v_pk_fma_f32 v[8:9], v[136:137], v[8:9], v[20:21]
	v_pk_add_f32 v[20:21], v[32:33], v[4:5]
	v_sub_f32_e32 v84, v32, v4
	v_sub_f32_e32 v85, v33, v5
	global_store_dwordx2 v[122:123], v[16:17], off offset:1536 sc1
	v_cvt_pk_bf16_f32 v16, v32, v33
	v_cvt_pk_bf16_f32 v17, v34, v35
	global_store_dwordx2 v[118:119], v[16:17], off sc1
	v_cvt_pk_bf16_f32 v4, v4, v5
	v_cvt_pk_bf16_f32 v5, v6, v7
	v_pk_fma_f32 v[46:47], v[138:139], v[46:47], v[18:19]
	v_pk_fma_f32 v[14:15], v[138:139], v[14:15], v[18:19]
	v_pk_add_f32 v[18:19], v[34:35], v[6:7]
	global_store_dwordx2 v[120:121], v[4:5], off sc1
	v_cvt_pk_bf16_f32 v4, v20, v21
	v_cvt_pk_bf16_f32 v5, v18, v19
	v_sub_f32_e32 v82, v34, v6
	v_sub_f32_e32 v83, v35, v7
	global_store_dwordx2 v[116:117], v[4:5], off sc1
	v_cvt_pk_bf16_f32 v4, v84, v85
	v_cvt_pk_bf16_f32 v5, v82, v83
	v_pk_fma_f32 v[42:43], v[134:135], v[42:43], v[22:23]
	global_store_dwordx2 v[114:115], v[4:5], off sc1
	v_cvt_pk_bf16_f32 v4, v40, v41
	v_cvt_pk_bf16_f32 v5, v42, v43
	v_pk_fma_f32 v[10:11], v[134:135], v[10:11], v[22:23]
	global_store_dwordx2 v[118:119], v[4:5], off offset:512 sc1
	v_cvt_pk_bf16_f32 v4, v8, v9
	v_cvt_pk_bf16_f32 v5, v10, v11
	v_pk_fma_f32 v[36:37], v[144:145], v[36:37], v[24:25]
	v_pk_fma_f32 v[0:1], v[144:145], v[0:1], v[24:25]
	v_pk_add_f32 v[22:23], v[42:43], v[10:11]
	v_pk_add_f32 v[24:25], v[40:41], v[8:9]
	global_store_dwordx2 v[120:121], v[4:5], off offset:512 sc1
	v_cvt_pk_bf16_f32 v4, v24, v25
	v_cvt_pk_bf16_f32 v5, v22, v23
	v_sub_f32_e32 v86, v42, v10
	v_sub_f32_e32 v87, v43, v11
	v_sub_f32_e32 v92, v40, v8
	v_sub_f32_e32 v93, v41, v9
	global_store_dwordx2 v[116:117], v[4:5], off offset:512 sc1
	v_cvt_pk_bf16_f32 v4, v92, v93
	v_cvt_pk_bf16_f32 v5, v86, v87
	global_store_dwordx2 v[114:115], v[4:5], off offset:512 sc1
	v_cvt_pk_bf16_f32 v4, v44, v45
	v_cvt_pk_bf16_f32 v5, v46, v47
	global_store_dwordx2 v[118:119], v[4:5], off offset:1024 sc1
	v_cvt_pk_bf16_f32 v4, v12, v13
	v_cvt_pk_bf16_f32 v5, v14, v15
	v_pk_fma_f32 v[38:39], v[142:143], v[38:39], v[26:27]
	v_pk_fma_f32 v[2:3], v[142:143], v[2:3], v[26:27]
	v_pk_add_f32 v[26:27], v[46:47], v[14:15]
	v_pk_add_f32 v[28:29], v[44:45], v[12:13]
	global_store_dwordx2 v[120:121], v[4:5], off offset:1024 sc1
	v_cvt_pk_bf16_f32 v4, v28, v29
	v_cvt_pk_bf16_f32 v5, v26, v27
	v_sub_f32_e32 v94, v46, v14
	v_sub_f32_e32 v130, v47, v15
	v_sub_f32_e32 v131, v44, v12
	v_sub_f32_e32 v132, v45, v13
	global_store_dwordx2 v[116:117], v[4:5], off offset:1024 sc1
	v_cvt_pk_bf16_f32 v4, v131, v132
	v_cvt_pk_bf16_f32 v5, v94, v130
	v_pk_add_f32 v[80:81], v[36:37], v[0:1]
	v_sub_f32_e32 v135, v36, v0
	v_sub_f32_e32 v136, v37, v1
	global_store_dwordx2 v[114:115], v[4:5], off offset:1024 sc1
	v_cvt_pk_bf16_f32 v4, v36, v37
	v_cvt_pk_bf16_f32 v5, v38, v39
	global_store_dwordx2 v[118:119], v[4:5], off offset:1536 sc1
	v_cvt_pk_bf16_f32 v0, v0, v1
	v_cvt_pk_bf16_f32 v1, v2, v3
	v_pk_add_f32 v[30:31], v[38:39], v[2:3]
	global_store_dwordx2 v[120:121], v[0:1], off offset:1536 sc1
	v_cvt_pk_bf16_f32 v0, v80, v81
	v_cvt_pk_bf16_f32 v1, v30, v31
	v_sub_f32_e32 v133, v38, v2
	v_sub_f32_e32 v134, v39, v3
	global_store_dwordx2 v[116:117], v[0:1], off offset:1536 sc1
	v_cvt_pk_bf16_f32 v0, v135, v136
	v_cvt_pk_bf16_f32 v1, v133, v134
	global_store_dwordx2 v[114:115], v[0:1], off offset:1536 sc1
	s_andn2_b64 exec, exec, s[22:23]
	s_cbranch_execnz .LBB0_99
